# same restructurings but barrier non-leaders poll their XCD release word as in the baseline
# speedup vs baseline: 1.0015x; 1.0015x over previous
; __device__ __forceinline__ unsigned xb_ld(unsigned* p)              { return __hip_atomic_load(p, __ATOMIC_RELAXED, __HIP_MEMORY_SCOPE_AGENT); }
; __device__ __forceinline__ unsigned xb_add(unsigned* p, unsigned v) { return __hip_atomic_fetch_add(p, v, __ATOMIC_RELAXED, __HIP_MEMORY_SCOPE_AGENT); }
; #define XB_SPIN(cond, bar) do { unsigned _sp = 0; while (cond) { __builtin_amdgcn_s_sleep(1); \
;     if ((++_sp & 255u) == 0u) { if (xb_ld(&(bar)[XB_TMO])) break; if (_sp > XB_SPIN_CAP) { atomicAdd(&(bar)[XB_TMO], 1u); break; } } } } while (0)
; __device__ __forceinline__ void xcd_barrier(const XcdBarrier& b) {
;     ...
;         const unsigned old = xb_add(&bar[XB_XSUB(b.x)], 1u);
;         const unsigned gen = old / nloc;
;         if (old + 1u == (gen + 1u) * nloc) {
;             __builtin_amdgcn_fence(__ATOMIC_RELEASE, "agent");
;             asm volatile("s_waitcnt vmcnt(0)" ::: "memory");
;             const unsigned og = xb_add(&bar[XB_TOP], 1u);
;             const unsigned tg = og / nx;
;             if (og + 1u == (tg + 1u) * nx) xb_add(&bar[XB_TOPGEN], 1u);
;             else XB_SPIN(xb_ld(&bar[XB_TOPGEN]) == tg, bar);
;             __builtin_amdgcn_fence(__ATOMIC_ACQUIRE, "agent");
;             xb_add(&bar[XB_XGEN(b.x)], 1u);
;             asm volatile("s_waitcnt vmcnt(0)" ::: "memory");
;         } else {
;             XB_SPIN(xb_ld(&bar[XB_XGEN(b.x)]) == gen, bar);
.LBB0_140:
	s_or_b64 exec, exec, s[10:11]
	v_cvt_f32_u32_e32 v4, v2
	s_waitcnt vmcnt(0)
	buffer_inv sc1
	v_readfirstlane_b32 s3, v3
	v_sub_u32_e32 v3, 0, v2
	v_rcp_iflag_f32_e32 v4, v4
	v_add_u32_e32 v5, s3, v1
	v_mul_f32_e32 v4, 0x4f7ffffe, v4
	v_cvt_u32_f32_e32 v4, v4
	v_mul_lo_u32 v1, v3, v4
	v_mul_hi_u32 v1, v4, v1
	v_add_u32_e32 v1, v4, v1
	v_mul_hi_u32 v1, v5, v1
	v_mul_lo_u32 v3, v1, v2
	v_sub_u32_e32 v3, v5, v3
	v_add_u32_e32 v4, 1, v1
	v_cmp_ge_u32_e32 vcc, v3, v2
	s_nop 1
	v_cndmask_b32_e32 v1, v1, v4, vcc
	v_sub_u32_e32 v4, v3, v2
	v_cndmask_b32_e32 v3, v3, v4, vcc
	v_add_u32_e32 v4, 1, v1
	v_cmp_ge_u32_e32 vcc, v3, v2
	v_add_u32_e32 v3, 1, v5
	s_nop 0
	v_cndmask_b32_e32 v1, v1, v4, vcc
	v_mul_lo_u32 v4, v2, v1
	v_add_u32_e32 v2, v4, v2
	v_cmp_ne_u32_e32 vcc, v3, v2
	s_and_saveexec_b64 s[8:9], vcc
	s_xor_b64 s[8:9], exec, s[8:9]
	s_cbranch_execz .LBB0_154
	s_waitcnt lgkmcnt(0)
	v_mov_b32_e32 v0, 0x2000
	global_load_dword v0, v0, s[6:7] offset:1024 sc1
	s_add_u32 s14, s6, 0x2400
	s_addc_u32 s15, s7, 0
	s_waitcnt vmcnt(0)
	v_cmp_eq_u32_e32 vcc, v0, v1
	s_and_saveexec_b64 s[10:11], vcc
	s_cbranch_execz .LBB0_153
	s_add_u32 s12, s30, 0x80200
	s_addc_u32 s13, s31, 0
	s_mov_b32 s3, 1
	s_mov_b64 s[16:17], 0
	v_mov_b32_e32 v0, 0
	s_branch .LBB0_144

; __device__ __forceinline__ unsigned xb_ld(unsigned* p)              { return __hip_atomic_load(p, __ATOMIC_RELAXED, __HIP_MEMORY_SCOPE_AGENT); }
; __device__ __forceinline__ unsigned xb_add(unsigned* p, unsigned v) { return __hip_atomic_fetch_add(p, v, __ATOMIC_RELAXED, __HIP_MEMORY_SCOPE_AGENT); }
; #define XB_SPIN(cond, bar) do { unsigned _sp = 0; while (cond) { __builtin_amdgcn_s_sleep(1); \
;     if ((++_sp & 255u) == 0u) { if (xb_ld(&(bar)[XB_TMO])) break; if (_sp > XB_SPIN_CAP) { atomicAdd(&(bar)[XB_TMO], 1u); break; } } } } while (0)
; __device__ __forceinline__ void xcd_barrier(const XcdBarrier& b) {
;     ...
;         const unsigned old = xb_add(&bar[XB_XSUB(b.x)], 1u);
;         const unsigned gen = old / nloc;
;         if (old + 1u == (gen + 1u) * nloc) {
;             __builtin_amdgcn_fence(__ATOMIC_RELEASE, "agent");
;             asm volatile("s_waitcnt vmcnt(0)" ::: "memory");
;             const unsigned og = xb_add(&bar[XB_TOP], 1u);
;             const unsigned tg = og / nx;
;             if (og + 1u == (tg + 1u) * nx) xb_add(&bar[XB_TOPGEN], 1u);
;             else XB_SPIN(xb_ld(&bar[XB_TOPGEN]) == tg, bar);
;             __builtin_amdgcn_fence(__ATOMIC_ACQUIRE, "agent");
;             xb_add(&bar[XB_XGEN(b.x)], 1u);
;             asm volatile("s_waitcnt vmcnt(0)" ::: "memory");
;         } else {
;             XB_SPIN(xb_ld(&bar[XB_XGEN(b.x)]) == gen, bar);
.LBB0_669:
	s_or_b64 exec, exec, s[8:9]
	v_cvt_f32_u32_e32 v4, v2
	s_waitcnt vmcnt(0)
	buffer_inv sc1
	v_readfirstlane_b32 s3, v3
	v_sub_u32_e32 v3, 0, v2
	v_rcp_iflag_f32_e32 v4, v4
	v_add_u32_e32 v5, s3, v1
	v_mul_f32_e32 v4, 0x4f7ffffe, v4
	v_cvt_u32_f32_e32 v4, v4
	v_mul_lo_u32 v1, v3, v4
	v_mul_hi_u32 v1, v4, v1
	v_add_u32_e32 v1, v4, v1
	v_mul_hi_u32 v1, v5, v1
	v_mul_lo_u32 v3, v1, v2
	v_sub_u32_e32 v3, v5, v3
	v_add_u32_e32 v4, 1, v1
	v_cmp_ge_u32_e32 vcc, v3, v2
	s_nop 1
	v_cndmask_b32_e32 v1, v1, v4, vcc
	v_sub_u32_e32 v4, v3, v2
	v_cndmask_b32_e32 v3, v3, v4, vcc
	v_add_u32_e32 v4, 1, v1
	v_cmp_ge_u32_e32 vcc, v3, v2
	v_add_u32_e32 v3, 1, v5
	s_nop 0
	v_cndmask_b32_e32 v1, v1, v4, vcc
	v_mul_lo_u32 v4, v2, v1
	v_add_u32_e32 v2, v4, v2
	v_cmp_ne_u32_e32 vcc, v3, v2
	s_and_saveexec_b64 s[6:7], vcc
	s_xor_b64 s[6:7], exec, s[6:7]
	s_cbranch_execz .LBB0_683
	s_waitcnt lgkmcnt(0)
	v_mov_b32_e32 v0, 0x2000
	global_load_dword v0, v0, s[4:5] offset:1024 sc1
	s_add_u32 s12, s4, 0x2400
	s_addc_u32 s13, s5, 0
	s_waitcnt vmcnt(0)
	v_cmp_eq_u32_e32 vcc, v0, v1
	s_and_saveexec_b64 s[8:9], vcc
	s_cbranch_execz .LBB0_682
	s_add_u32 s10, s30, 0x80200
	s_addc_u32 s11, s31, 0
	s_mov_b32 s3, 1
	s_mov_b64 s[14:15], 0
	v_mov_b32_e32 v0, 0
	s_branch .LBB0_673

; __device__ __forceinline__ unsigned xb_ld(unsigned* p)              { return __hip_atomic_load(p, __ATOMIC_RELAXED, __HIP_MEMORY_SCOPE_AGENT); }
; __device__ __forceinline__ unsigned xb_add(unsigned* p, unsigned v) { return __hip_atomic_fetch_add(p, v, __ATOMIC_RELAXED, __HIP_MEMORY_SCOPE_AGENT); }
; #define XB_SPIN(cond, bar) do { unsigned _sp = 0; while (cond) { __builtin_amdgcn_s_sleep(1); \
;     if ((++_sp & 255u) == 0u) { if (xb_ld(&(bar)[XB_TMO])) break; if (_sp > XB_SPIN_CAP) { atomicAdd(&(bar)[XB_TMO], 1u); break; } } } } while (0)
; __device__ __forceinline__ void xcd_barrier(const XcdBarrier& b) {
;     ...
;         const unsigned old = xb_add(&bar[XB_XSUB(b.x)], 1u);
;         const unsigned gen = old / nloc;
;         if (old + 1u == (gen + 1u) * nloc) {
;             __builtin_amdgcn_fence(__ATOMIC_RELEASE, "agent");
;             asm volatile("s_waitcnt vmcnt(0)" ::: "memory");
;             const unsigned og = xb_add(&bar[XB_TOP], 1u);
;             const unsigned tg = og / nx;
;             if (og + 1u == (tg + 1u) * nx) xb_add(&bar[XB_TOPGEN], 1u);
;             else XB_SPIN(xb_ld(&bar[XB_TOPGEN]) == tg, bar);
;             __builtin_amdgcn_fence(__ATOMIC_ACQUIRE, "agent");
;             xb_add(&bar[XB_XGEN(b.x)], 1u);
;             asm volatile("s_waitcnt vmcnt(0)" ::: "memory");
;         } else {
;             XB_SPIN(xb_ld(&bar[XB_XGEN(b.x)]) == gen, bar);
.LBB0_1506:
	s_or_b64 exec, exec, s[6:7]
	v_cvt_f32_u32_e32 v4, v2
	s_waitcnt vmcnt(0)
	buffer_inv sc1
	v_readfirstlane_b32 s4, v3
	v_sub_u32_e32 v3, 0, v2
	v_rcp_iflag_f32_e32 v4, v4
	v_add_u32_e32 v5, s4, v1
	v_mul_f32_e32 v4, 0x4f7ffffe, v4
	v_cvt_u32_f32_e32 v4, v4
	v_mul_lo_u32 v1, v3, v4
	v_mul_hi_u32 v1, v4, v1
	v_add_u32_e32 v1, v4, v1
	v_mul_hi_u32 v1, v5, v1
	v_mul_lo_u32 v3, v1, v2
	v_sub_u32_e32 v3, v5, v3
	v_add_u32_e32 v4, 1, v1
	v_cmp_ge_u32_e32 vcc, v3, v2
	s_nop 1
	v_cndmask_b32_e32 v1, v1, v4, vcc
	v_sub_u32_e32 v4, v3, v2
	v_cndmask_b32_e32 v3, v3, v4, vcc
	v_add_u32_e32 v4, 1, v1
	v_cmp_ge_u32_e32 vcc, v3, v2
	v_add_u32_e32 v3, 1, v5
	s_nop 0
	v_cndmask_b32_e32 v1, v1, v4, vcc
	v_mul_lo_u32 v4, v2, v1
	v_add_u32_e32 v2, v4, v2
	v_cmp_ne_u32_e32 vcc, v3, v2
	s_and_saveexec_b64 s[4:5], vcc
	s_xor_b64 s[4:5], exec, s[4:5]
	s_cbranch_execz .LBB0_1520
	s_waitcnt lgkmcnt(0)
	v_mov_b32_e32 v0, 0x2000
	global_load_dword v0, v0, s[2:3] offset:1024 sc1
	s_add_u32 s10, s2, 0x2400
	s_addc_u32 s11, s3, 0
	s_waitcnt vmcnt(0)
	v_cmp_eq_u32_e32 vcc, v0, v1
	s_and_saveexec_b64 s[6:7], vcc
	s_cbranch_execz .LBB0_1519
	s_add_u32 s8, s30, 0x80200
	s_addc_u32 s9, s31, 0
	s_mov_b32 s22, 1
	s_mov_b64 s[12:13], 0
	v_mov_b32_e32 v0, 0
	s_branch .LBB0_1510
